# baseline (speedup 1.0000x reference)
.LBB0_117:
	s_or_b64 exec, exec, s[46:47]
	s_lshr_b32 s46, s42, 3
	s_ashr_i32 s43, s42, 31
	s_lshl_b64 s[44:45], s[42:43], 12
	s_and_b32 s43, s46, 3
	s_lshl_b32 s46, s43, 14
	s_lshl_b32 s47, s43, 9
	s_lshl_b32 s43, s43, 8
	s_lshl_b64 s[28:29], s[28:29], 2
	s_add_u32 s28, s33, s28
	s_addc_u32 s29, s50, s29
	s_lshl_b32 s48, s51, 2
	s_add_u32 s28, s28, s48
	s_addc_u32 s29, s29, 0
	s_add_u32 s28, s28, s40
	s_addc_u32 s29, s29, s41
	global_load_dwordx4 v[42:45], v99, s[28:29]
	s_lshl_b64 s[28:29], s[26:27], 22
	s_or_b32 s28, s28, s46
	v_lshl_add_u64 v[10:11], v[60:61], 0, s[44:45]
	v_lshl_add_u64 v[84:85], s[28:29], 0, v[70:71]
	s_lshl_b64 s[28:29], s[26:27], 17
	v_lshlrev_b64 v[82:83], 6, v[10:11]
	s_or_b32 s28, s28, s47
	v_mov_b32_e32 v10, 0x1800000
	v_lshl_add_u64 v[86:87], s[28:29], 0, v[72:73]
	s_mul_i32 s46, s26, 0x1800000
	v_mad_i64_i32 v[10:11], s[28:29], s26, v10, v[74:75]
	v_lshl_add_u64 v[6:7], v[8:9], 0, v[6:7]
	s_mul_hi_i32 s27, s26, 0x1800000
	v_lshl_add_u64 v[88:89], v[6:7], 1, v[10:11]
	s_or_b32 s26, s46, s43
	v_mov_b32_e32 v10, 0
	v_lshl_add_u64 v[90:91], s[26:27], 0, v[76:77]
	s_mov_b32 s43, 63
	v_mov_b32_e32 v11, v10
	v_mov_b32_e32 v12, v10
	v_mov_b32_e32 v13, v10
	v_mov_b32_e32 v14, v10
	v_mov_b32_e32 v15, v10
	v_mov_b32_e32 v16, v10
	v_mov_b32_e32 v17, v10
	s_mov_b32 s60, 0xa400
	s_waitcnt vmcnt(0)

.LBB0_126:
	s_nop 7
	s_waitcnt lgkmcnt(4)
	v_cndmask_b32_e64 v46, v46, 0, s[18:19]
	v_cvt_pk_bf16_f32 v46, v46, v46
	ds_write_b16 v100, v46 offset:57888
	v_cndmask_b32_e64 v46, v47, 0, s[20:21]
	v_cvt_pk_bf16_f32 v46, v46, v46
	ds_write_b16 v100, v46 offset:58032
	v_cndmask_b32_e64 v46, v48, 0, s[22:23]
	v_cvt_pk_bf16_f32 v46, v46, v46
	ds_write_b16 v100, v46 offset:58176
	v_cndmask_b32_e64 v46, v49, 0, s[24:25]
	v_cvt_pk_bf16_f32 v46, v46, v46
	ds_write_b16 v100, v46 offset:58320
	s_mov_b64 s[46:47], 0x1000
	s_add_i32 s43, s43, -1
	v_lshl_add_u64 v[86:87], v[86:87], 0, s[96:97]
	s_cmp_eq_u32 s43, 0
	s_waitcnt lgkmcnt(8)
	v_mfma_f32_16x16x32_bf16 v[46:49], v[110:113], v[182:185], 0
	v_mfma_f32_16x16x32_bf16 v[46:49], v[114:117], v[186:189], v[46:49]
	v_mfma_f32_16x16x32_bf16 v[46:49], v[118:121], v[190:193], v[46:49]
	v_mfma_f32_16x16x32_bf16 v[46:49], v[122:125], v[194:197], v[46:49]
	s_waitcnt lgkmcnt(0)
	s_barrier
	ds_read_b128 v[142:145], v92 offset:57856
	ds_read_b128 v[146:149], v93 offset:53248
	ds_read_b128 v[150:153], v92 offset:57920
	ds_read_b128 v[154:157], v93 offset:53312
	ds_read_b128 v[158:161], v68 offset:34816
	ds_read_b128 v[162:165], v69 offset:53248
	ds_read_b128 v[166:169], v69 offset:55552
	ds_read_b128 v[170:173], v68 offset:34880
	ds_read_b128 v[174:177], v69 offset:53312
	ds_read_b128 v[178:181], v69 offset:55616
	s_waitcnt lgkmcnt(8)
	v_mfma_f32_16x16x32_bf16 v[46:49], v[142:145], v[146:149], v[46:49]
	s_waitcnt lgkmcnt(6)
	v_mfma_f32_16x16x32_bf16 v[46:49], v[150:153], v[154:157], v[46:49]
	s_waitcnt lgkmcnt(4)
	v_mfma_f32_16x16x32_bf16 v[10:13], v[158:161], v[162:165], v[10:13]
	s_waitcnt lgkmcnt(3)
	v_mfma_f32_16x16x32_bf16 v[14:17], v[158:161], v[166:169], v[14:17]
	s_waitcnt lgkmcnt(1)
	v_mfma_f32_16x16x32_bf16 v[10:13], v[170:173], v[174:177], v[10:13]
	s_waitcnt lgkmcnt(0)
	v_mfma_f32_16x16x32_bf16 v[14:17], v[170:173], v[178:181], v[14:17]
	s_nop 1
	v_bfe_u32 v50, v46, 16, 1
	v_add3_u32 v46, v46, v50, s93
	v_lshl_add_u64 v[50:51], v[66:67], 0, v[82:83]
	global_store_short_d16_hi v[50:51], v46, off
	v_bfe_u32 v46, v47, 16, 1
	v_add3_u32 v50, v47, v46, s93
	v_or_b32_e32 v46, 64, v82
	v_mov_b32_e32 v47, v83
	v_lshl_add_u64 v[46:47], v[66:67], 0, v[46:47]
	global_store_short_d16_hi v[46:47], v50, off
	v_bfe_u32 v46, v48, 16, 1
	v_add3_u32 v48, v48, v46, s93
	v_or_b32_e32 v46, 0x80, v82
	v_mov_b32_e32 v47, v83
	v_lshl_add_u64 v[46:47], v[66:67], 0, v[46:47]
	global_store_short_d16_hi v[46:47], v48, off
	v_bfe_u32 v46, v49, 16, 1
	v_add3_u32 v48, v49, v46, s93
	v_or_b32_e32 v46, 0xc0, v82
	v_mov_b32_e32 v47, v83
	v_lshl_add_u64 v[46:47], v[66:67], 0, v[46:47]
	global_store_short_d16_hi v[46:47], v48, off
	v_lshl_add_u64 v[82:83], v[82:83], 0, s[46:47]
	s_mov_b64 s[46:47], 0x10000
	v_lshl_add_u64 v[84:85], v[84:85], 0, s[46:47]
	s_mov_b64 s[46:47], 0x60000
	v_lshl_add_u64 v[88:89], v[88:89], 0, s[46:47]
	v_lshl_add_u64 v[90:91], v[90:91], 0, s[46:47]
	s_nop 1
	v_pk_mul_f32 v[12:13], v[44:45], v[12:13]
	v_pk_mul_f32 v[10:11], v[42:43], v[10:11]
	s_nop 2
	v_pk_mul_f32 v[16:17], v[44:45], v[16:17]
	v_pk_mul_f32 v[14:15], v[42:43], v[14:15]
	v_cvt_pk_bf16_f32 v42, v10, v11
	v_cvt_pk_bf16_f32 v43, v12, v13
	v_cvt_pk_bf16_f32 v45, v16, v17
	s_nop 0
	v_cvt_pk_bf16_f32 v44, v14, v15
	ds_write_b64 v94, v[42:43]
	ds_write_b64 v94, v[44:45] offset:4352
	v_add_u32_e32 v57, s60, v57
	v_add_u32_e32 v63, s60, v63
	v_add_u32_e32 v93, s60, v93
	v_add_u32_e32 v68, s60, v68
	v_add_u32_e32 v69, s60, v69
	s_mul_i32 s60, s60, -1
	s_cbranch_scc1 .LBB0_128
	s_waitcnt vmcnt(4)
	v_mov_b64_e32 v[44:45], v[8:9]
	v_mov_b64_e32 v[42:43], v[6:7]
	s_branch .LBB0_118
